# v14 with the loader's after-barrier wait also counting out the conversion stores of the iteration
# baseline (speedup 1.0000x reference)
.LBB0_208:
	s_mov_b32 s67, s53
	s_cmp_eq_u32 s53, 1
	s_cbranch_scc0 .Lcis_b_done
	s_waitcnt vmcnt(9)
	s_cmp_eq_u32 s56, 1
	s_cbranch_scc0 .Lcis_b_nogs
	v_pk_mul_f32 v[232:233], v[232:233], v[208:209]
	v_pk_mul_f32 v[234:235], v[234:235], v[210:211]
	v_pk_mul_f32 v[236:237], v[236:237], v[212:213]
	v_pk_mul_f32 v[238:239], v[238:239], v[214:215]
	v_pk_mul_f32 v[240:241], v[240:241], v[216:217]
	v_pk_mul_f32 v[242:243], v[242:243], v[218:219]
	v_pk_mul_f32 v[244:245], v[244:245], v[220:221]
	v_pk_mul_f32 v[246:247], v[246:247], v[222:223]

.LBB0_212:
	s_or_b64 exec, exec, s[22:23]
	s_and_b32 s22, s24, 0x800
	s_addk_i32 s24, 0x800
	v_add_u32_e32 v40, s22, v171
	s_add_u32 s20, s20, 32
	ds_read_b64 v[40:41], v40
	s_addc_u32 s21, s21, 0
	s_mov_b64 s[22:23], 0x48000
	s_add_i32 s19, s19, 1
	s_waitcnt lgkmcnt(0)
	v_cvt_pk_bf16_f32 v42, v40, v41
	v_lshl_add_u64 v[40:41], s[14:15], 0, v[148:149]
	v_lshl_add_u64 v[148:149], v[148:149], 0, s[92:93]
	v_lshl_add_u64 v[150:151], v[150:151], 0, s[92:93]
	v_lshl_add_u64 v[154:155], v[154:155], 0, s[22:23]
	s_cmpk_eq_i32 s20, 0xfa0
	global_store_dword v[40:41], v42, off
	s_barrier
	s_cbranch_scc1 .LBB0_214
	s_cmp_eq_u32 s53, 1
	s_cbranch_scc0 .Lcis_w1
	s_cmp_eq_u32 s56, 1
	s_cbranch_scc1 .Lcis_w21
	s_cmp_eq_u32 s56, 2
	s_cbranch_scc1 .Lcis_w5
	s_cmp_eq_u32 s67, 1
	s_cbranch_scc1 .Lcis_w17_st
	s_waitcnt vmcnt(17)
	s_branch .Lcis_wd
.Lcis_w17_st:
	s_waitcnt vmcnt(19)
	s_branch .Lcis_wd
.Lcis_w21:
	s_cmp_eq_u32 s67, 1
	s_cbranch_scc1 .Lcis_w21_st
	s_waitcnt vmcnt(21)
	s_branch .Lcis_wd
.Lcis_w21_st:
	s_waitcnt vmcnt(23)
	s_branch .Lcis_wd
.Lcis_w5:
	s_cmp_eq_u32 s67, 1
	s_cbranch_scc1 .Lcis_w5_st
	s_waitcnt vmcnt(5)
	s_branch .Lcis_wd
.Lcis_w5_st:
	s_waitcnt vmcnt(7)
	s_branch .Lcis_wd
.Lcis_w1:
	s_cmp_eq_u32 s67, 1
	s_cbranch_scc1 .Lcis_w1_st
	s_waitcnt vmcnt(1)
	s_branch .Lcis_wd
.Lcis_w1_st:
	s_waitcnt vmcnt(3)
